# plain (L2-resident) ring stores; prep prefetch+early poll+deferred publish; fetch early peeks, counted waits, deferred DONE atomic
# speedup vs baseline: 1.0119x; 1.0119x over previous
; #define LAS __attribute__((address_space(3)))
; __device__ void phase_rwkv_dist(const Params& p, LAS unsigned char* lds, int wg, int nwg) {
;     ...
;                 float ss = 0.f, bo = 0.f;
; #pragma unroll
;                 for (int nt = 0; nt < 4; ++nt) { const f32x4 muk = *(LAS const f32x4*)(cq + 6 * 64 + 16 * nt), kkc = *(LAS const f32x4*)(cq + 2 * 64 + 16 * nt);
;                     const f32x4 kc = up4(nX[4 + nt][0]); f32x4 kq = up4(nX[4 + nt][1]); if (first) kq = zero4; const f32x4 kkv = (kc + (kq - kc) * muk) * kkc; ss += sumsq4(kkv); }
;                 ss += __shfl_xor(ss, 16); ss += __shfl_xor(ss, 32);
;                 const float rn = __builtin_amdgcn_rsqf(fmaxf(ss, 1e-24f));
;                 if (ci >= RD_NG) { unsigned sp = 0; while (!dead && __hip_atomic_load(DONE + bh * 512 + (ci - RD_NG), __ATOMIC_RELAXED, __HIP_MEMORY_SCOPE_AGENT) < 256u) { __builtin_amdgcn_s_sleep(2); if (++sp > RD_SPIN_MAX) { if (lane == 0) atomicAdd(ERR, 1u); dead = true; } } }
;                 const int so = ringbase + (ci % RD_NG) * RD_SLOTG;
;                 bf16x4 qa[4], qb[4], qk[4], qr[4];
; #pragma unroll
;                 for (int nt = 0; nt < 4; ++nt) {
;                     const f32x4 w0 = *(LAS const f32x4*)(cq + 0 * 64 + 16 * nt), a0 = *(LAS const f32x4*)(cq + 1 * 64 + 16 * nt);
;                     f32x4 lw, ag;
; #pragma unroll
;                     for (int i = 0; i < 4; ++i) { lw[i] = -0.60653066f * __builtin_amdgcn_rcpf(1.f + __expf(-(w0[i] + accw[nt][i]))); ag[i] = __builtin_amdgcn_rcpf(1.f + __expf(-(a0[i] + acca[nt][i]))); }
;                     const f32x4 mur = *(LAS const f32x4*)(cq + 5 * 64 + 16 * nt), muk = *(LAS const f32x4*)(cq + 6 * 64 + 16 * nt), kkc = *(LAS const f32x4*)(cq + 2 * 64 + 16 * nt), kac = *(LAS const f32x4*)(cq + 3 * 64 + 16 * nt), rkc = *(LAS const f32x4*)(cq + 4 * 64 + 16 * nt);
;                     const f32x4 rc = up4(nX[nt][0]), kc = up4(nX[4 + nt][0]); f32x4 rp = up4(nX[nt][1]), kq = up4(nX[4 + nt][1]); if (first) { rp = zero4; kq = zero4; }
;                     const f32x4 r4 = rc + (rp - rc) * mur, k4 = kc + (kq - kc) * muk;
;                     const f32x4 kn = k4 * kkc * rn, kp = k4 * (1.f + (ag - 1.f) * kac);
;                     const f32x4 b4_ = r4 * kp * rkc; bo += (b4_.x + b4_.y) + (b4_.z + b4_.w);
;                     f32x4 G = lw;
; #pragma unroll
.LBB0_651:
	s_waitcnt lgkmcnt(0)
	v_add_f32_e32 v0, v0, v100
	ds_read_b128 v[100:103], v139
	ds_read_b128 v[142:145], v139 offset:256
	v_lshlrev_b32_e32 v168, 16, v64
	v_and_b32_e32 v64, 0xffff0000, v64
	v_lshlrev_b32_e32 v169, 16, v65
	s_waitcnt lgkmcnt(1)
	v_add_f32_e32 v52, v52, v100
	v_mul_f32_e32 v52, 0xbfb8aa3b, v52
	v_exp_f32_e32 v52, v52
	v_and_b32_e32 v65, 0xffff0000, v65
	v_lshlrev_b32_e32 v166, 16, v60
	v_and_b32_e32 v167, 0xffff0000, v60
	v_add_f32_e32 v52, 1.0, v52
	v_rcp_f32_e32 v157, v52
	s_waitcnt lgkmcnt(0)
	v_add_f32_e32 v52, v56, v142
	v_mul_f32_e32 v52, 0xbfb8aa3b, v52
	v_exp_f32_e32 v52, v52
	v_lshlrev_b32_e32 v60, 16, v61
	v_and_b32_e32 v61, 0xffff0000, v61
	v_cndmask_b32_e64 v177, v169, 0, s[38:39]
	v_add_f32_e32 v52, 1.0, v52
	v_rcp_f32_e32 v146, v52
	v_add_f32_e32 v52, v53, v101
	v_mul_f32_e32 v52, 0xbfb8aa3b, v52
	v_exp_f32_e32 v52, v52
	v_cndmask_b32_e64 v169, v65, 0, s[38:39]
	v_cndmask_b32_e64 v168, v168, 0, s[38:39]
	v_cndmask_b32_e64 v64, v64, 0, s[38:39]
	v_add_f32_e32 v52, 1.0, v52
	v_rcp_f32_e32 v170, v52
	v_add_f32_e32 v52, v57, v143
	v_mul_f32_e32 v52, 0xbfb8aa3b, v52
	v_exp_f32_e32 v52, v52
	v_sub_f32_e32 v65, v64, v167
	v_sub_f32_e32 v64, v168, v166
	v_sub_f32_e32 v169, v169, v61
	v_add_f32_e32 v52, 1.0, v52
	v_rcp_f32_e32 v147, v52
	v_add_f32_e32 v52, v54, v102
	v_mul_f32_e32 v52, 0xbfb8aa3b, v52
	v_exp_f32_e32 v52, v52
	v_sub_f32_e32 v168, v177, v60
	v_mul_f32_e32 v164, 0xbf1b4598, v157
	v_mul_f32_e32 v171, 0xbf1b4598, v170
	v_add_f32_e32 v52, 1.0, v52
	v_rcp_f32_e32 v172, v52
	v_add_f32_e32 v52, v58, v144
	v_mul_f32_e32 v52, 0xbfb8aa3b, v52
	v_exp_f32_e32 v52, v52
	v_mul_f32_e32 v173, 0xbf1b4598, v172
	v_max_f32_e32 v0, 0x179abe15, v0
	v_rsq_f32_e32 v0, v0
	v_add_f32_e32 v52, 1.0, v52
	v_rcp_f32_e32 v162, v52
	v_add_f32_e32 v52, v55, v103
	v_mul_f32_e32 v52, 0xbfb8aa3b, v52
	v_exp_f32_e32 v52, v52
	s_lshl_b32 s2, s62, 4
	s_ashr_i32 s3, s2, 31
	v_lshl_add_u64 v[108:109], v[2:3], 0, s[2:3]
	v_add_f32_e32 v52, 1.0, v52
	v_rcp_f32_e32 v174, v52
	v_add_f32_e32 v52, v59, v145
	v_mul_f32_e32 v52, 0xbfb8aa3b, v52
	v_exp_f32_e32 v52, v52
	v_mul_f32_e32 v176, 0xbf1b4598, v174
	s_mul_hi_i32 s2, s62, 0x92492493
	s_add_i32 s2, s2, s62
	v_add_f32_e32 v52, 1.0, v52
	v_rcp_f32_e32 v163, v52
	ds_read_b128 v[52:55], v139 offset:1280
	ds_read_b128 v[56:59], v139 offset:1536
	ds_read_b128 v[100:103], v139 offset:512
	ds_read_b128 v[142:145], v139 offset:768
	ds_read_b128 v[158:161], v139 offset:1024
	s_waitcnt lgkmcnt(4)
	v_pk_fma_f32 v[54:55], v[168:169], v[54:55], v[60:61]
	v_pk_fma_f32 v[60:61], v[64:65], v[52:53], v[166:167]
	s_waitcnt lgkmcnt(3)
	v_pk_fma_f32 v[52:53], v[96:97], v[58:59], v[94:95]
	v_pk_fma_f32 v[56:57], v[98:99], v[56:57], v[92:93]
	v_pk_add_f32 v[92:93], v[162:163], -1.0 op_sel_hi:[1,0]
	v_pk_add_f32 v[94:95], v[146:147], -1.0 op_sel_hi:[1,0]
	s_waitcnt lgkmcnt(1)
	v_pk_fma_f32 v[92:93], v[144:145], v[92:93], 1.0 op_sel_hi:[1,1,0]
	v_pk_fma_f32 v[94:95], v[142:143], v[94:95], 1.0 op_sel_hi:[1,1,0]
	v_pk_mul_f32 v[64:65], v[100:101], v[56:57]
	v_pk_mul_f32 v[96:97], v[52:53], v[92:93]
	v_pk_mul_f32 v[56:57], v[56:57], v[94:95]
	v_pk_mul_f32 v[58:59], v[102:103], v[52:53]
	v_pk_mul_f32 v[52:53], v[60:61], v[56:57]
	v_pk_mul_f32 v[92:93], v[54:55], v[96:97]
	s_waitcnt lgkmcnt(0)
	v_pk_mul_f32 v[52:53], v[158:159], v[52:53]
	v_pk_mul_f32 v[92:93], v[160:161], v[92:93]
	v_add_f32_e32 v52, v52, v53
	v_add_f32_e32 v53, v92, v93
	v_add_f32_e32 v101, v52, v53
	v_mov_b32_dpp v52, v164 row_shr:1 row_mask:0xf bank_mask:0xf bound_ctrl:1
	v_fmac_f32_e32 v52, 0xbf1b4598, v157
	v_mov_b32_e32 v100, 1.0
	v_pk_mul_f32 v[98:99], v[0:1], v[64:65] op_sel_hi:[0,1]
	v_add_f32_dpp v52, v52, v52 row_shr:2 row_mask:0xf bank_mask:0xf bound_ctrl:1
	v_pk_fma_f32 v[64:65], v[0:1], v[64:65], 0 op_sel_hi:[0,1,0] neg_lo:[1,0,0] neg_hi:[1,0,0]
	s_lshr_b32 s3, s2, 31
	v_add_f32_dpp v52, v52, v52 row_shr:4 row_mask:0xf bank_mask:0xf bound_ctrl:1
	s_lshr_b32 s2, s2, 5
	s_add_i32 s2, s2, s3
	v_add_f32_dpp v92, v52, v52 row_shr:8 row_mask:0xf bank_mask:0xf bound_ctrl:1
	v_mov_b32_dpp v52, v171 row_shr:1 row_mask:0xf bank_mask:0xf bound_ctrl:1
	v_fmac_f32_e32 v52, 0xbf1b4598, v170
	v_mul_f32_e32 v92, 0x3fb8aa3b, v92
	v_exp_f32_e32 v92, v92
	v_add_f32_dpp v52, v52, v52 row_shr:2 row_mask:0xf bank_mask:0xf bound_ctrl:1
	s_mul_i32 s2, s2, 56
	s_sub_i32 s2, s62, s2
	v_add_f32_dpp v52, v52, v52 row_shr:4 row_mask:0xf bank_mask:0xf bound_ctrl:1
	v_rcp_f32_e32 v102, v92
	v_mov_b32_dpp v100, v92 row_shr:1 row_mask:0xf bank_mask:0xf
	v_add_f32_dpp v93, v52, v52 row_shr:8 row_mask:0xf bank_mask:0xf bound_ctrl:1
	v_mov_b32_dpp v52, v173 row_shr:1 row_mask:0xf bank_mask:0xf bound_ctrl:1
	v_fmac_f32_e32 v52, 0xbf1b4598, v172
	v_mul_f32_e32 v93, 0x3fb8aa3b, v93
	v_exp_f32_e32 v93, v93
	v_add_f32_dpp v52, v52, v52 row_shr:2 row_mask:0xf bank_mask:0xf bound_ctrl:1
	v_pk_mul_f32 v[64:65], v[64:65], v[100:101] op_sel_hi:[1,0]
	s_mulk_i32 s2, 0x2900
	v_add_f32_dpp v52, v52, v52 row_shr:4 row_mask:0xf bank_mask:0xf bound_ctrl:1
	v_rcp_f32_e32 v103, v93
	v_cvt_pk_bf16_f32 v64, v64, v65
	v_add_f32_dpp v94, v52, v52 row_shr:8 row_mask:0xf bank_mask:0xf bound_ctrl:1
	v_mov_b32_dpp v52, v176 row_shr:1 row_mask:0xf bank_mask:0xf bound_ctrl:1
	v_fmac_f32_e32 v52, 0xbf1b4598, v174
	v_mul_f32_e32 v94, 0x3fb8aa3b, v94
	v_exp_f32_e32 v94, v94
	v_add_f32_dpp v52, v52, v52 row_shr:2 row_mask:0xf bank_mask:0xf bound_ctrl:1
	v_pk_mul_f32 v[56:57], v[56:57], v[102:103]
	s_add_i32 s2, s2, s80
	v_add_f32_dpp v52, v52, v52 row_shr:4 row_mask:0xf bank_mask:0xf bound_ctrl:1
	v_rcp_f32_e32 v144, v94
	v_cvt_pk_bf16_f32 v56, v56, v57
	v_add_f32_dpp v95, v52, v52 row_shr:8 row_mask:0xf bank_mask:0xf bound_ctrl:1
; #define LAS __attribute__((address_space(3)))
; #define MFMA16(a, b, c) __builtin_amdgcn_mfma_f32_16x16x16bf16_1k(a, b, c, 0, 0, 0)
; __device__ void phase_rwkv_dist(const Params& p, LAS unsigned char* lds, int wg, int nwg) {
;     ...
;                 for (int nt = 0; nt < 4; ++nt) {
;                     const f32x4 w0 = *(LAS const f32x4*)(cq + 0 * 64 + 16 * nt), a0 = *(LAS const f32x4*)(cq + 1 * 64 + 16 * nt);
;                     f32x4 lw, ag;
; #pragma unroll
;                     for (int i = 0; i < 4; ++i) { lw[i] = -0.60653066f * __builtin_amdgcn_rcpf(1.f + __expf(-(w0[i] + accw[nt][i]))); ag[i] = __builtin_amdgcn_rcpf(1.f + __expf(-(a0[i] + acca[nt][i]))); }
;                     const f32x4 mur = *(LAS const f32x4*)(cq + 5 * 64 + 16 * nt), muk = *(LAS const f32x4*)(cq + 6 * 64 + 16 * nt), kkc = *(LAS const f32x4*)(cq + 2 * 64 + 16 * nt), kac = *(LAS const f32x4*)(cq + 3 * 64 + 16 * nt), rkc = *(LAS const f32x4*)(cq + 4 * 64 + 16 * nt);
;                     const f32x4 rc = up4(nX[nt][0]), kc = up4(nX[4 + nt][0]); f32x4 rp = up4(nX[nt][1]), kq = up4(nX[4 + nt][1]); if (first) { rp = zero4; kq = zero4; }
;                     const f32x4 r4 = rc + (rp - rc) * mur, k4 = kc + (kq - kc) * muk;
;                     const f32x4 kn = k4 * kkc * rn, kp = k4 * (1.f + (ag - 1.f) * kac);
;                     const f32x4 b4_ = r4 * kp * rkc; bo += (b4_.x + b4_.y) + (b4_.z + b4_.w);
;                     f32x4 G = lw;
; #pragma unroll
;                     for (int i = 0; i < 4; ++i) { float g = G[i]; g += dpp_f<0x111>(g); g += dpp_f<0x112>(g); g += dpp_f<0x114>(g); g += dpp_f<0x118>(g); G[i] = g; }
;                     f32x4 eG, eGx, eI;
; #pragma unroll
;                     for (int i = 0; i < 4; ++i) { eG[i] = __expf(G[i]); eGx[i] = __builtin_bit_cast(float, __builtin_amdgcn_update_dpp(0x3F800000, __builtin_bit_cast(int, eG[i]), 0x111, 0xf, 0xf, false)); eI[i] = __builtin_amdgcn_rcpf(eG[i]); }
;                     qa[nt] = pk4((zero4 - kn) * eGx); qb[nt] = pk4(kn * ag * eI); qk[nt] = pk4(kp * eI); qr[nt] = pk4(r4 * eG);
;                     __builtin_amdgcn_raw_buffer_store_b128(__builtin_bit_cast(u32x4, eG), rsWS, (r == 15) ? (16 * nt + 4 * q) * 4 : 0x7ffffff0, so + 10240, 16);
;                     const f32x4 d1 = MFMA16(qb[nt], ident, zero4), d2 = MFMA16(qk[nt], ident, zero4);
	v_mul_f32_e32 v95, 0x3fb8aa3b, v95
	v_exp_f32_e32 v95, v95
	v_pk_mul_f32 v[52:53], v[0:1], v[58:59] op_sel_hi:[0,1]
	v_pk_fma_f32 v[58:59], v[0:1], v[58:59], 0 op_sel_hi:[0,1,0] neg_lo:[1,0,0] neg_hi:[1,0,0]
	v_pk_mul_f32 v[58:59], v[58:59], v[100:101] op_sel_hi:[1,0]
	v_rcp_f32_e32 v145, v95
	v_cvt_pk_bf16_f32 v65, v58, v59
	v_pk_mul_f32 v[58:59], v[98:99], v[146:147]
	v_pk_mul_f32 v[52:53], v[52:53], v[162:163]
	s_add_i32 s6, s2, 0x2800
	v_pk_mul_f32 v[98:99], v[52:53], v[144:145]
	v_pk_mul_f32 v[52:53], v[58:59], v[102:103]
	v_pk_mul_f32 v[58:59], v[96:97], v[144:145]
	v_cvt_pk_bf16_f32 v52, v52, v53
	v_cvt_pk_bf16_f32 v53, v98, v99
	v_cvt_pk_bf16_f32 v57, v58, v59
	v_pk_mul_f32 v[54:55], v[54:55], v[94:95]
	v_pk_mul_f32 v[58:59], v[60:61], v[92:93]
	buffer_store_dwordx4 v[92:95], v210, s[52:55], s6 offen
	v_mfma_f32_16x16x16_bf16 v[92:95], v[52:53], v[150:151], 0
	s_add_i32 s3, s2, 0x1000
	v_cvt_pk_bf16_f32 v60, v58, v59
	v_cvt_pk_bf16_f32 v61, v54, v55
	v_mfma_f32_16x16x16_bf16 v[96:99], v[56:57], v[150:151], 0
	v_lshlrev_b32_e32 v162, 16, v66
	s_nop 2
	v_cvt_pk_bf16_f32 v92, v92, v93
	v_cvt_pk_bf16_f32 v93, v94, v95
	v_and_b32_e32 v66, 0xffff0000, v66
	v_add_f32_e32 v142, 0, v101
	v_cvt_pk_bf16_f32 v94, v96, v97
	v_cvt_pk_bf16_f32 v95, v98, v99
	buffer_store_dwordx4 v[92:95], v196, s[52:55], s3 offen
	ds_read_b128 v[92:95], v139 offset:64
	ds_read_b128 v[96:99], v139 offset:320
	v_lshlrev_b32_e32 v160, 16, v62
	v_and_b32_e32 v161, 0xffff0000, v62
	v_lshlrev_b32_e32 v163, 16, v67
	s_waitcnt lgkmcnt(1)
	v_add_f32_e32 v54, v84, v92
	v_add_f32_e32 v55, v85, v93
	v_add_f32_e32 v58, v86, v94
	v_add_f32_e32 v59, v87, v95
	v_mul_f32_e32 v54, 0xbfb8aa3b, v54
	v_mul_f32_e32 v55, 0xbfb8aa3b, v55
	v_mul_f32_e32 v58, 0xbfb8aa3b, v58
	v_mul_f32_e32 v59, 0xbfb8aa3b, v59
	v_exp_f32_e32 v54, v54
	v_exp_f32_e32 v55, v55
	v_exp_f32_e32 v58, v58
	v_exp_f32_e32 v59, v59
	v_add_f32_e32 v54, 1.0, v54
	v_add_f32_e32 v55, 1.0, v55
	v_add_f32_e32 v58, 1.0, v58
	v_add_f32_e32 v59, 1.0, v59
	v_rcp_f32_e32 v143, v54
	s_waitcnt lgkmcnt(0)
	v_add_f32_e32 v54, v88, v96
	v_rcp_f32_e32 v145, v55
	v_add_f32_e32 v55, v89, v97
	v_rcp_f32_e32 v147, v58
	v_add_f32_e32 v58, v90, v98
	v_rcp_f32_e32 v158, v59
	v_add_f32_e32 v59, v91, v99
	v_mul_f32_e32 v54, 0xbfb8aa3b, v54
	v_mul_f32_e32 v55, 0xbfb8aa3b, v55
	v_mul_f32_e32 v58, 0xbfb8aa3b, v58
	v_mul_f32_e32 v59, 0xbfb8aa3b, v59
	v_exp_f32_e32 v54, v54
	v_exp_f32_e32 v55, v55
	v_exp_f32_e32 v58, v58
	v_exp_f32_e32 v59, v59
	v_add_f32_e32 v54, 1.0, v54
	v_add_f32_e32 v55, 1.0, v55
	v_add_f32_e32 v58, 1.0, v58
	v_add_f32_e32 v59, 1.0, v59
	v_rcp_f32_e32 v54, v54
	v_rcp_f32_e32 v55, v55
	v_rcp_f32_e32 v58, v58
	v_rcp_f32_e32 v59, v59
	ds_read_b128 v[84:87], v139 offset:1344
	ds_read_b128 v[88:91], v139 offset:1600
	ds_read_b128 v[92:95], v139 offset:576
	ds_read_b128 v[96:99], v139 offset:832
	ds_read_b128 v[100:103], v139 offset:1088
	v_and_b32_e32 v67, 0xffff0000, v67
	v_cndmask_b32_e64 v162, v162, 0, s[38:39]
	v_cndmask_b32_e64 v66, v66, 0, s[38:39]
	v_lshlrev_b32_e32 v62, 16, v63
	v_and_b32_e32 v63, 0xffff0000, v63
	v_cndmask_b32_e64 v164, v163, 0, s[38:39]
	v_cndmask_b32_e64 v163, v67, 0, s[38:39]
	v_sub_f32_e32 v67, v66, v161
	v_sub_f32_e32 v66, v162, v160
	v_sub_f32_e32 v163, v163, v63
	v_sub_f32_e32 v162, v164, v62
	s_waitcnt lgkmcnt(4)
	v_pk_fma_f32 v[160:161], v[66:67], v[84:85], v[160:161]
	s_waitcnt lgkmcnt(3)
	v_pk_fma_f32 v[84:85], v[136:137], v[88:89], v[130:131]
	v_pk_fma_f32 v[62:63], v[162:163], v[86:87], v[62:63]
	v_pk_fma_f32 v[66:67], v[134:135], v[90:91], v[132:133]
	s_waitcnt lgkmcnt(2)
	v_pk_mul_f32 v[90:91], v[92:93], v[84:85]
	v_pk_add_f32 v[86:87], v[58:59], -1.0 op_sel_hi:[1,0]
	v_pk_add_f32 v[92:93], v[54:55], -1.0 op_sel_hi:[1,0]
	s_waitcnt lgkmcnt(1)
	v_pk_fma_f32 v[86:87], v[98:99], v[86:87], 1.0 op_sel_hi:[1,1,0]
	v_pk_fma_f32 v[92:93], v[96:97], v[92:93], 1.0 op_sel_hi:[1,1,0]
	v_pk_mul_f32 v[88:89], v[94:95], v[66:67]
	v_pk_mul_f32 v[94:95], v[66:67], v[86:87]
	v_pk_mul_f32 v[92:93], v[84:85], v[92:93]
	v_pk_mul_f32 v[84:85], v[62:63], v[94:95]
	v_pk_mul_f32 v[66:67], v[160:161], v[92:93]
	v_mul_f32_e32 v146, 0xbf1b4598, v145
	s_waitcnt lgkmcnt(0)
	v_pk_mul_f32 v[84:85], v[102:103], v[84:85]
	v_pk_mul_f32 v[66:67], v[100:101], v[66:67]
	v_mul_f32_e32 v157, 0xbf1b4598, v147
	v_add_f32_e32 v66, v66, v67
	v_add_f32_e32 v67, v84, v85
	v_mov_b32_dpp v84, v146 row_shr:1 row_mask:0xf bank_mask:0xf bound_ctrl:1
	v_fmac_f32_e32 v84, 0xbf1b4598, v145
	v_mul_f32_e32 v144, 0xbf1b4598, v143
	v_mul_f32_e32 v159, 0xbf1b4598, v158
	v_add_f32_dpp v84, v84, v84 row_shr:2 row_mask:0xf bank_mask:0xf bound_ctrl:1
	v_add_f32_e32 v67, v66, v67
	v_mov_b32_dpp v66, v144 row_shr:1 row_mask:0xf bank_mask:0xf bound_ctrl:1
	v_add_f32_dpp v84, v84, v84 row_shr:4 row_mask:0xf bank_mask:0xf bound_ctrl:1
	v_fmac_f32_e32 v66, 0xbf1b4598, v143
	v_pk_mul_f32 v[96:97], v[0:1], v[88:89] op_sel_hi:[0,1]
	v_add_f32_dpp v85, v84, v84 row_shr:8 row_mask:0xf bank_mask:0xf bound_ctrl:1
	v_mov_b32_dpp v84, v157 row_shr:1 row_mask:0xf bank_mask:0xf bound_ctrl:1
	v_fmac_f32_e32 v84, 0xbf1b4598, v147
	v_add_f32_dpp v66, v66, v66 row_shr:2 row_mask:0xf bank_mask:0xf bound_ctrl:1
	v_mul_f32_e32 v85, 0x3fb8aa3b, v85
	v_add_f32_dpp v84, v84, v84 row_shr:2 row_mask:0xf bank_mask:0xf bound_ctrl:1
	v_add_f32_dpp v66, v66, v66 row_shr:4 row_mask:0xf bank_mask:0xf bound_ctrl:1
	v_exp_f32_e32 v85, v85
	v_add_f32_dpp v84, v84, v84 row_shr:4 row_mask:0xf bank_mask:0xf bound_ctrl:1
	v_add_f32_dpp v66, v66, v66 row_shr:8 row_mask:0xf bank_mask:0xf bound_ctrl:1
	v_mul_f32_e32 v66, 0x3fb8aa3b, v66
	v_add_f32_dpp v86, v84, v84 row_shr:8 row_mask:0xf bank_mask:0xf bound_ctrl:1
; #define LAS __attribute__((address_space(3)))
; #define MFMA16(a, b, c) __builtin_amdgcn_mfma_f32_16x16x16bf16_1k(a, b, c, 0, 0, 0)
; __device__ void phase_rwkv_dist(const Params& p, LAS unsigned char* lds, int wg, int nwg) {
;     ...
;                 for (int nt = 0; nt < 4; ++nt) {
;                     const f32x4 w0 = *(LAS const f32x4*)(cq + 0 * 64 + 16 * nt), a0 = *(LAS const f32x4*)(cq + 1 * 64 + 16 * nt);
;                     f32x4 lw, ag;
; #pragma unroll
;                     for (int i = 0; i < 4; ++i) { lw[i] = -0.60653066f * __builtin_amdgcn_rcpf(1.f + __expf(-(w0[i] + accw[nt][i]))); ag[i] = __builtin_amdgcn_rcpf(1.f + __expf(-(a0[i] + acca[nt][i]))); }
;                     const f32x4 mur = *(LAS const f32x4*)(cq + 5 * 64 + 16 * nt), muk = *(LAS const f32x4*)(cq + 6 * 64 + 16 * nt), kkc = *(LAS const f32x4*)(cq + 2 * 64 + 16 * nt), kac = *(LAS const f32x4*)(cq + 3 * 64 + 16 * nt), rkc = *(LAS const f32x4*)(cq + 4 * 64 + 16 * nt);
;                     const f32x4 rc = up4(nX[nt][0]), kc = up4(nX[4 + nt][0]); f32x4 rp = up4(nX[nt][1]), kq = up4(nX[4 + nt][1]); if (first) { rp = zero4; kq = zero4; }
;                     const f32x4 r4 = rc + (rp - rc) * mur, k4 = kc + (kq - kc) * muk;
;                     const f32x4 kn = k4 * kkc * rn, kp = k4 * (1.f + (ag - 1.f) * kac);
;                     const f32x4 b4_ = r4 * kp * rkc; bo += (b4_.x + b4_.y) + (b4_.z + b4_.w);
;                     f32x4 G = lw;
; #pragma unroll
;                     for (int i = 0; i < 4; ++i) { float g = G[i]; g += dpp_f<0x111>(g); g += dpp_f<0x112>(g); g += dpp_f<0x114>(g); g += dpp_f<0x118>(g); G[i] = g; }
;                     f32x4 eG, eGx, eI;
; #pragma unroll
;                     for (int i = 0; i < 4; ++i) { eG[i] = __expf(G[i]); eGx[i] = __builtin_bit_cast(float, __builtin_amdgcn_update_dpp(0x3F800000, __builtin_bit_cast(int, eG[i]), 0x111, 0xf, 0xf, false)); eI[i] = __builtin_amdgcn_rcpf(eG[i]); }
;                     qa[nt] = pk4((zero4 - kn) * eGx); qb[nt] = pk4(kn * ag * eI); qk[nt] = pk4(kp * eI); qr[nt] = pk4(r4 * eG);
;                     __builtin_amdgcn_raw_buffer_store_b128(__builtin_bit_cast(u32x4, eG), rsWS, (r == 15) ? (16 * nt + 4 * q) * 4 : 0x7ffffff0, so + 10240, 16);
;                     const f32x4 d1 = MFMA16(qb[nt], ident, zero4), d2 = MFMA16(qk[nt], ident, zero4);
	v_mov_b32_dpp v84, v159 row_shr:1 row_mask:0xf bank_mask:0xf bound_ctrl:1
	v_fmac_f32_e32 v84, 0xbf1b4598, v158
	v_mul_f32_e32 v86, 0x3fb8aa3b, v86
	v_exp_f32_e32 v86, v86
	v_add_f32_dpp v84, v84, v84 row_shr:2 row_mask:0xf bank_mask:0xf bound_ctrl:1
	v_rcp_f32_e32 v101, v85
	v_pk_mul_f32 v[98:99], v[0:1], v[90:91] op_sel_hi:[0,1]
	v_add_f32_dpp v84, v84, v84 row_shr:4 row_mask:0xf bank_mask:0xf bound_ctrl:1
	v_rcp_f32_e32 v102, v86
	v_pk_fma_f32 v[88:89], v[0:1], v[88:89], 0 op_sel_hi:[0,1,0] neg_lo:[1,0,0] neg_hi:[1,0,0]
	v_add_f32_dpp v87, v84, v84 row_shr:8 row_mask:0xf bank_mask:0xf bound_ctrl:1
	v_mul_f32_e32 v87, 0x3fb8aa3b, v87
	v_exp_f32_e32 v84, v66
	v_exp_f32_e32 v87, v87
	v_mov_b32_e32 v66, 1.0
	v_pk_fma_f32 v[90:91], v[0:1], v[90:91], 0 op_sel_hi:[0,1,0] neg_lo:[1,0,0] neg_hi:[1,0,0]
	v_rcp_f32_e32 v100, v84
	v_rcp_f32_e32 v103, v87
	v_mov_b32_dpp v66, v84 row_shr:1 row_mask:0xf bank_mask:0xf
	v_pk_mul_f32 v[54:55], v[98:99], v[54:55]
	v_pk_mul_f32 v[58:59], v[96:97], v[58:59]
	v_add_f32_e32 v130, v142, v67
	v_pk_mul_f32 v[88:89], v[88:89], v[66:67] op_sel_hi:[1,0]
	v_pk_mul_f32 v[66:67], v[90:91], v[66:67] op_sel_hi:[1,0]
	v_pk_mul_f32 v[58:59], v[58:59], v[102:103]
	v_pk_mul_f32 v[54:55], v[54:55], v[100:101]
	v_cvt_pk_bf16_f32 v66, v66, v67
	v_cvt_pk_bf16_f32 v67, v88, v89
	v_cvt_pk_bf16_f32 v54, v54, v55
	v_cvt_pk_bf16_f32 v55, v58, v59
	v_pk_mul_f32 v[88:89], v[94:95], v[102:103]
	v_pk_mul_f32 v[58:59], v[92:93], v[100:101]
	buffer_store_dwordx4 v[84:87], v211, s[52:55], s6 offen
	v_cvt_pk_bf16_f32 v58, v58, v59
	v_cvt_pk_bf16_f32 v59, v88, v89
	v_pk_mul_f32 v[88:89], v[62:63], v[86:87]
	v_pk_mul_f32 v[62:63], v[160:161], v[84:85]
	v_mfma_f32_16x16x16_bf16 v[84:87], v[54:55], v[150:151], 0
	v_cvt_pk_bf16_f32 v62, v62, v63
	v_cvt_pk_bf16_f32 v63, v88, v89
	v_lshlrev_b32_e32 v100, 16, v118
	v_mfma_f32_16x16x16_bf16 v[88:91], v[58:59], v[150:151], 0
	v_and_b32_e32 v101, 0xffff0000, v118
	s_nop 2
	v_cvt_pk_bf16_f32 v84, v84, v85
	v_cvt_pk_bf16_f32 v85, v86, v87
	v_lshlrev_b32_e32 v102, 16, v119
	v_and_b32_e32 v103, 0xffff0000, v119
	v_cvt_pk_bf16_f32 v86, v88, v89
	v_cvt_pk_bf16_f32 v87, v90, v91
	buffer_store_dwordx4 v[84:87], v197, s[52:55], s3 offen
	ds_read_b128 v[84:87], v139 offset:128
	ds_read_b128 v[88:91], v139 offset:384
	v_lshlrev_b32_e32 v118, 16, v120
	v_and_b32_e32 v119, 0xffff0000, v120
	v_lshlrev_b32_e32 v120, 16, v121
	s_waitcnt lgkmcnt(1)
	v_add_f32_e32 v76, v76, v84
	v_mul_f32_e32 v76, 0xbfb8aa3b, v76
	v_exp_f32_e32 v76, v76
	v_and_b32_e32 v121, 0xffff0000, v121
	v_cndmask_b32_e64 v118, v118, 0, s[38:39]
	v_cndmask_b32_e64 v119, v119, 0, s[38:39]
	v_add_f32_e32 v76, 1.0, v76
	v_rcp_f32_e32 v131, v76
	s_waitcnt lgkmcnt(0)
	v_add_f32_e32 v76, v80, v88
	v_mul_f32_e32 v76, 0xbfb8aa3b, v76
	v_exp_f32_e32 v76, v76
	v_cndmask_b32_e64 v120, v120, 0, s[38:39]
	v_cndmask_b32_e64 v121, v121, 0, s[38:39]
	v_sub_f32_e32 v119, v119, v101
	v_add_f32_e32 v76, 1.0, v76
	v_rcp_f32_e32 v96, v76
	v_add_f32_e32 v76, v77, v85
	v_mul_f32_e32 v76, 0xbfb8aa3b, v76
	v_exp_f32_e32 v76, v76
	v_sub_f32_e32 v118, v118, v100
	v_sub_f32_e32 v121, v121, v103
	v_sub_f32_e32 v120, v120, v102
	v_add_f32_e32 v76, 1.0, v76
	v_rcp_f32_e32 v133, v76
	v_add_f32_e32 v76, v81, v89
	v_mul_f32_e32 v76, 0xbfb8aa3b, v76
	v_exp_f32_e32 v76, v76
	v_mul_f32_e32 v132, 0xbf1b4598, v131
	v_mul_f32_e32 v134, 0xbf1b4598, v133
	v_add_f32_e32 v76, 1.0, v76
	v_rcp_f32_e32 v97, v76
	v_add_f32_e32 v76, v78, v86
	v_mul_f32_e32 v76, 0xbfb8aa3b, v76
	v_exp_f32_e32 v76, v76
	s_nop 0
	v_add_f32_e32 v76, 1.0, v76
	v_rcp_f32_e32 v135, v76
	v_add_f32_e32 v76, v82, v90
	v_mul_f32_e32 v76, 0xbfb8aa3b, v76
	v_exp_f32_e32 v76, v76
	v_mul_f32_e32 v136, 0xbf1b4598, v135
	v_add_f32_e32 v76, 1.0, v76
	v_rcp_f32_e32 v98, v76
	v_add_f32_e32 v76, v79, v87
	v_mul_f32_e32 v76, 0xbfb8aa3b, v76
	v_exp_f32_e32 v76, v76
	s_nop 0
	v_add_f32_e32 v76, 1.0, v76
	v_rcp_f32_e32 v137, v76
	v_add_f32_e32 v76, v83, v91
	v_mul_f32_e32 v76, 0xbfb8aa3b, v76
	v_exp_f32_e32 v76, v76
	v_mul_f32_e32 v142, 0xbf1b4598, v137
	v_add_f32_e32 v76, 1.0, v76
	v_rcp_f32_e32 v99, v76
	ds_read_b128 v[76:79], v139 offset:1408
	ds_read_b128 v[80:83], v139 offset:1664
	ds_read_b128 v[84:87], v139 offset:640
	ds_read_b128 v[88:91], v139 offset:896
	ds_read_b128 v[92:95], v139 offset:1152
	s_waitcnt lgkmcnt(4)
	v_pk_fma_f32 v[100:101], v[118:119], v[76:77], v[100:101]
	s_waitcnt lgkmcnt(3)
	v_pk_fma_f32 v[76:77], v[126:127], v[82:83], v[124:125]
	v_pk_fma_f32 v[78:79], v[120:121], v[78:79], v[102:103]
	s_waitcnt lgkmcnt(2)
	v_pk_mul_f32 v[82:83], v[86:87], v[76:77]
	v_pk_add_f32 v[86:87], v[98:99], -1.0 op_sel_hi:[1,0]
	v_pk_add_f32 v[102:103], v[96:97], -1.0 op_sel_hi:[1,0]
	v_pk_fma_f32 v[80:81], v[128:129], v[80:81], v[122:123]
	s_waitcnt lgkmcnt(1)
	v_pk_fma_f32 v[88:89], v[88:89], v[102:103], 1.0 op_sel_hi:[1,1,0]
	v_pk_fma_f32 v[86:87], v[90:91], v[86:87], 1.0 op_sel_hi:[1,1,0]
	v_pk_mul_f32 v[84:85], v[84:85], v[80:81]
	v_pk_mul_f32 v[102:103], v[76:77], v[86:87]
	v_pk_mul_f32 v[80:81], v[80:81], v[88:89]
	v_pk_mul_f32 v[86:87], v[78:79], v[102:103]
	v_pk_mul_f32 v[76:77], v[100:101], v[80:81]
	s_waitcnt lgkmcnt(0)
; #define LAS __attribute__((address_space(3)))
; #define MFMA16(a, b, c) __builtin_amdgcn_mfma_f32_16x16x16bf16_1k(a, b, c, 0, 0, 0)
; __device__ void phase_rwkv_dist(const Params& p, LAS unsigned char* lds, int wg, int nwg) {
;     ...
;                 for (int nt = 0; nt < 4; ++nt) {
;                     const f32x4 w0 = *(LAS const f32x4*)(cq + 0 * 64 + 16 * nt), a0 = *(LAS const f32x4*)(cq + 1 * 64 + 16 * nt);
;                     f32x4 lw, ag;
; #pragma unroll
;                     for (int i = 0; i < 4; ++i) { lw[i] = -0.60653066f * __builtin_amdgcn_rcpf(1.f + __expf(-(w0[i] + accw[nt][i]))); ag[i] = __builtin_amdgcn_rcpf(1.f + __expf(-(a0[i] + acca[nt][i]))); }
;                     const f32x4 mur = *(LAS const f32x4*)(cq + 5 * 64 + 16 * nt), muk = *(LAS const f32x4*)(cq + 6 * 64 + 16 * nt), kkc = *(LAS const f32x4*)(cq + 2 * 64 + 16 * nt), kac = *(LAS const f32x4*)(cq + 3 * 64 + 16 * nt), rkc = *(LAS const f32x4*)(cq + 4 * 64 + 16 * nt);
;                     const f32x4 rc = up4(nX[nt][0]), kc = up4(nX[4 + nt][0]); f32x4 rp = up4(nX[nt][1]), kq = up4(nX[4 + nt][1]); if (first) { rp = zero4; kq = zero4; }
;                     const f32x4 r4 = rc + (rp - rc) * mur, k4 = kc + (kq - kc) * muk;
;                     const f32x4 kn = k4 * kkc * rn, kp = k4 * (1.f + (ag - 1.f) * kac);
;                     const f32x4 b4_ = r4 * kp * rkc; bo += (b4_.x + b4_.y) + (b4_.z + b4_.w);
;                     f32x4 G = lw;
; #pragma unroll
;                     for (int i = 0; i < 4; ++i) { float g = G[i]; g += dpp_f<0x111>(g); g += dpp_f<0x112>(g); g += dpp_f<0x114>(g); g += dpp_f<0x118>(g); G[i] = g; }
;                     f32x4 eG, eGx, eI;
; #pragma unroll
;                     for (int i = 0; i < 4; ++i) { eG[i] = __expf(G[i]); eGx[i] = __builtin_bit_cast(float, __builtin_amdgcn_update_dpp(0x3F800000, __builtin_bit_cast(int, eG[i]), 0x111, 0xf, 0xf, false)); eI[i] = __builtin_amdgcn_rcpf(eG[i]); }
;                     qa[nt] = pk4((zero4 - kn) * eGx); qb[nt] = pk4(kn * ag * eI); qk[nt] = pk4(kp * eI); qr[nt] = pk4(r4 * eG);
;                     __builtin_amdgcn_raw_buffer_store_b128(__builtin_bit_cast(u32x4, eG), rsWS, (r == 15) ? (16 * nt + 4 * q) * 4 : 0x7ffffff0, so + 10240, 16);
;                     const f32x4 d1 = MFMA16(qb[nt], ident, zero4), d2 = MFMA16(qk[nt], ident, zero4);
	v_pk_mul_f32 v[86:87], v[94:95], v[86:87]
	v_pk_mul_f32 v[76:77], v[92:93], v[76:77]
	v_mov_b32_e32 v88, 1.0
	v_add_f32_e32 v76, v76, v77
	v_add_f32_e32 v77, v86, v87
	v_add_f32_e32 v86, v76, v77
	v_mov_b32_dpp v76, v132 row_shr:1 row_mask:0xf bank_mask:0xf bound_ctrl:1
	v_fmac_f32_e32 v76, 0xbf1b4598, v131
	v_pk_mul_f32 v[94:95], v[0:1], v[84:85] op_sel_hi:[0,1]
	v_pk_fma_f32 v[84:85], v[0:1], v[84:85], 0 op_sel_hi:[0,1,0] neg_lo:[1,0,0] neg_hi:[1,0,0]
	v_add_f32_dpp v76, v76, v76 row_shr:2 row_mask:0xf bank_mask:0xf bound_ctrl:1
	v_lshlrev_b32_e32 v123, 16, v106
	v_and_b32_e32 v106, 0xffff0000, v106
	v_add_f32_dpp v76, v76, v76 row_shr:4 row_mask:0xf bank_mask:0xf bound_ctrl:1
	v_lshlrev_b32_e32 v126, 16, v107
	v_and_b32_e32 v107, 0xffff0000, v107
	v_add_f32_dpp v87, v76, v76 row_shr:8 row_mask:0xf bank_mask:0xf bound_ctrl:1
	v_mov_b32_dpp v76, v134 row_shr:1 row_mask:0xf bank_mask:0xf bound_ctrl:1
	v_fmac_f32_e32 v76, 0xbf1b4598, v133
	v_mul_f32_e32 v87, 0x3fb8aa3b, v87
	v_exp_f32_e32 v90, v87
	v_add_f32_dpp v76, v76, v76 row_shr:2 row_mask:0xf bank_mask:0xf bound_ctrl:1
	v_lshlrev_b32_e32 v124, 16, v104
	v_and_b32_e32 v125, 0xffff0000, v104
	v_add_f32_dpp v76, v76, v76 row_shr:4 row_mask:0xf bank_mask:0xf bound_ctrl:1
	v_rcp_f32_e32 v118, v90
	v_mov_b32_dpp v88, v90 row_shr:1 row_mask:0xf bank_mask:0xf
	v_add_f32_dpp v89, v76, v76 row_shr:8 row_mask:0xf bank_mask:0xf bound_ctrl:1
	v_mov_b32_dpp v76, v136 row_shr:1 row_mask:0xf bank_mask:0xf bound_ctrl:1
	v_fmac_f32_e32 v76, 0xbf1b4598, v135
	v_mul_f32_e32 v87, 0x3fb8aa3b, v89
	v_exp_f32_e32 v91, v87
	v_add_f32_dpp v76, v76, v76 row_shr:2 row_mask:0xf bank_mask:0xf bound_ctrl:1
	v_pk_mul_f32 v[84:85], v[84:85], v[88:89] op_sel_hi:[1,0]
	v_lshlrev_b32_e32 v104, 16, v105
	v_add_f32_dpp v76, v76, v76 row_shr:4 row_mask:0xf bank_mask:0xf bound_ctrl:1
	v_rcp_f32_e32 v119, v91
	v_and_b32_e32 v105, 0xffff0000, v105
	v_add_f32_dpp v92, v76, v76 row_shr:8 row_mask:0xf bank_mask:0xf bound_ctrl:1
	v_mov_b32_dpp v76, v142 row_shr:1 row_mask:0xf bank_mask:0xf bound_ctrl:1
	v_fmac_f32_e32 v76, 0xbf1b4598, v137
	v_mul_f32_e32 v87, 0x3fb8aa3b, v92
	v_exp_f32_e32 v92, v87
	v_add_f32_dpp v76, v76, v76 row_shr:2 row_mask:0xf bank_mask:0xf bound_ctrl:1
	v_pk_mul_f32 v[80:81], v[80:81], v[118:119]
	v_cndmask_b32_e64 v126, v126, 0, s[38:39]
	v_add_f32_dpp v76, v76, v76 row_shr:4 row_mask:0xf bank_mask:0xf bound_ctrl:1
	v_rcp_f32_e32 v120, v92
	v_cvt_pk_bf16_f32 v80, v80, v81
	v_add_f32_dpp v93, v76, v76 row_shr:8 row_mask:0xf bank_mask:0xf bound_ctrl:1
	v_mul_f32_e32 v87, 0x3fb8aa3b, v93
	v_exp_f32_e32 v93, v87
	v_pk_mul_f32 v[76:77], v[0:1], v[82:83] op_sel_hi:[0,1]
	v_pk_fma_f32 v[82:83], v[0:1], v[82:83], 0 op_sel_hi:[0,1,0] neg_lo:[1,0,0] neg_hi:[1,0,0]
	v_pk_mul_f32 v[82:83], v[82:83], v[88:89] op_sel_hi:[1,0]
	v_rcp_f32_e32 v121, v93
	v_cvt_pk_bf16_f32 v89, v82, v83
	v_pk_mul_f32 v[82:83], v[94:95], v[96:97]
	v_pk_mul_f32 v[76:77], v[76:77], v[98:99]
	v_cvt_pk_bf16_f32 v88, v84, v85
	v_pk_mul_f32 v[84:85], v[76:77], v[120:121]
	v_pk_mul_f32 v[76:77], v[82:83], v[118:119]
	v_pk_mul_f32 v[82:83], v[102:103], v[120:121]
	v_cvt_pk_bf16_f32 v76, v76, v77
	v_cvt_pk_bf16_f32 v77, v84, v85
	v_cvt_pk_bf16_f32 v81, v82, v83
	v_pk_mul_f32 v[78:79], v[78:79], v[92:93]
	v_pk_mul_f32 v[82:83], v[100:101], v[90:91]
	buffer_store_dwordx4 v[90:93], v212, s[52:55], s6 offen
	v_mfma_f32_16x16x16_bf16 v[90:93], v[76:77], v[150:151], 0
	v_cvt_pk_bf16_f32 v85, v78, v79
	v_cvt_pk_bf16_f32 v84, v82, v83
	v_cndmask_b32_e64 v127, v107, 0, s[38:39]
	v_mfma_f32_16x16x16_bf16 v[94:97], v[80:81], v[150:151], 0
	v_cndmask_b32_e64 v123, v123, 0, s[38:39]
	s_nop 2
	v_cvt_pk_bf16_f32 v90, v90, v91
	v_cvt_pk_bf16_f32 v91, v92, v93
	v_cndmask_b32_e64 v106, v106, 0, s[38:39]
	v_sub_f32_e32 v107, v106, v125
	v_cvt_pk_bf16_f32 v92, v94, v95
	v_cvt_pk_bf16_f32 v93, v96, v97
	buffer_store_dwordx4 v[90:93], v213, s[52:55], s3 offen
	ds_read_b128 v[90:93], v139 offset:192
	ds_read_b128 v[94:97], v139 offset:448
	v_sub_f32_e32 v106, v123, v124
	v_sub_f32_e32 v127, v127, v105
	v_sub_f32_e32 v126, v126, v104
	s_waitcnt lgkmcnt(1)
	v_add_f32_e32 v68, v68, v90
	v_mul_f32_e32 v68, 0xbfb8aa3b, v68
	v_exp_f32_e32 v68, v68
	v_add_f32_e32 v86, v130, v86
	v_add_f32_e32 v68, 1.0, v68
	v_rcp_f32_e32 v87, v68
	s_waitcnt lgkmcnt(0)
	v_add_f32_e32 v68, v72, v94
	v_mul_f32_e32 v68, 0xbfb8aa3b, v68
	v_exp_f32_e32 v68, v68
	v_mul_f32_e32 v102, 0xbf1b4598, v87
	v_add_f32_e32 v68, 1.0, v68
	v_rcp_f32_e32 v78, v68
	v_add_f32_e32 v68, v69, v91
	v_mul_f32_e32 v68, 0xbfb8aa3b, v68
	v_exp_f32_e32 v68, v68
	s_nop 0
	v_add_f32_e32 v68, 1.0, v68
	v_rcp_f32_e32 v103, v68
	v_add_f32_e32 v68, v73, v95
	v_mul_f32_e32 v68, 0xbfb8aa3b, v68
	v_exp_f32_e32 v68, v68
	v_mul_f32_e32 v118, 0xbf1b4598, v103
	v_add_f32_e32 v68, 1.0, v68
	v_rcp_f32_e32 v79, v68
	v_add_f32_e32 v68, v70, v92
	v_mul_f32_e32 v68, 0xbfb8aa3b, v68
	v_exp_f32_e32 v68, v68
	s_nop 0
	v_add_f32_e32 v68, 1.0, v68
	v_rcp_f32_e32 v119, v68
	v_add_f32_e32 v68, v74, v96
	v_mul_f32_e32 v68, 0xbfb8aa3b, v68
	v_exp_f32_e32 v68, v68
	v_mul_f32_e32 v120, 0xbf1b4598, v119
	v_add_f32_e32 v68, 1.0, v68
	v_rcp_f32_e32 v82, v68
	v_add_f32_e32 v68, v71, v93
	v_mul_f32_e32 v68, 0xbfb8aa3b, v68
	v_exp_f32_e32 v68, v68
	s_nop 0
	v_add_f32_e32 v68, 1.0, v68
	v_rcp_f32_e32 v121, v68
	v_add_f32_e32 v68, v75, v97
	v_mul_f32_e32 v68, 0xbfb8aa3b, v68
	v_exp_f32_e32 v68, v68
	v_mul_f32_e32 v122, 0xbf1b4598, v121
	v_add_f32_e32 v68, 1.0, v68
	v_rcp_f32_e32 v83, v68
	ds_read_b128 v[68:71], v139 offset:1472
	ds_read_b128 v[72:75], v139 offset:1728
	ds_read_b128 v[90:93], v139 offset:704
	ds_read_b128 v[94:97], v139 offset:960
	ds_read_b128 v[98:101], v139 offset:1216
	s_waitcnt lgkmcnt(4)
; #define LAS __attribute__((address_space(3)))
; #define MFMA16(a, b, c) __builtin_amdgcn_mfma_f32_16x16x16bf16_1k(a, b, c, 0, 0, 0)
; __device__ void phase_rwkv_dist(const Params& p, LAS unsigned char* lds, int wg, int nwg) {
;     ...
;                 for (int nt = 0; nt < 4; ++nt) {
;                     const f32x4 w0 = *(LAS const f32x4*)(cq + 0 * 64 + 16 * nt), a0 = *(LAS const f32x4*)(cq + 1 * 64 + 16 * nt);
;                     f32x4 lw, ag;
; #pragma unroll
;                     for (int i = 0; i < 4; ++i) { lw[i] = -0.60653066f * __builtin_amdgcn_rcpf(1.f + __expf(-(w0[i] + accw[nt][i]))); ag[i] = __builtin_amdgcn_rcpf(1.f + __expf(-(a0[i] + acca[nt][i]))); }
;                     const f32x4 mur = *(LAS const f32x4*)(cq + 5 * 64 + 16 * nt), muk = *(LAS const f32x4*)(cq + 6 * 64 + 16 * nt), kkc = *(LAS const f32x4*)(cq + 2 * 64 + 16 * nt), kac = *(LAS const f32x4*)(cq + 3 * 64 + 16 * nt), rkc = *(LAS const f32x4*)(cq + 4 * 64 + 16 * nt);
;                     const f32x4 rc = up4(nX[nt][0]), kc = up4(nX[4 + nt][0]); f32x4 rp = up4(nX[nt][1]), kq = up4(nX[4 + nt][1]); if (first) { rp = zero4; kq = zero4; }
;                     const f32x4 r4 = rc + (rp - rc) * mur, k4 = kc + (kq - kc) * muk;
;                     const f32x4 kn = k4 * kkc * rn, kp = k4 * (1.f + (ag - 1.f) * kac);
;                     const f32x4 b4_ = r4 * kp * rkc; bo += (b4_.x + b4_.y) + (b4_.z + b4_.w);
;                     f32x4 G = lw;
; #pragma unroll
;                     for (int i = 0; i < 4; ++i) { float g = G[i]; g += dpp_f<0x111>(g); g += dpp_f<0x112>(g); g += dpp_f<0x114>(g); g += dpp_f<0x118>(g); G[i] = g; }
;                     f32x4 eG, eGx, eI;
; #pragma unroll
;                     for (int i = 0; i < 4; ++i) { eG[i] = __expf(G[i]); eGx[i] = __builtin_bit_cast(float, __builtin_amdgcn_update_dpp(0x3F800000, __builtin_bit_cast(int, eG[i]), 0x111, 0xf, 0xf, false)); eI[i] = __builtin_amdgcn_rcpf(eG[i]); }
;                     qa[nt] = pk4((zero4 - kn) * eGx); qb[nt] = pk4(kn * ag * eI); qk[nt] = pk4(kp * eI); qr[nt] = pk4(r4 * eG);
;                     __builtin_amdgcn_raw_buffer_store_b128(__builtin_bit_cast(u32x4, eG), rsWS, (r == 15) ? (16 * nt + 4 * q) * 4 : 0x7ffffff0, so + 10240, 16);
;                     const f32x4 d1 = MFMA16(qb[nt], ident, zero4), d2 = MFMA16(qk[nt], ident, zero4);
	v_pk_fma_f32 v[104:105], v[126:127], v[70:71], v[104:105]
	v_pk_fma_f32 v[106:107], v[106:107], v[68:69], v[124:125]
	s_waitcnt lgkmcnt(3)
	v_pk_fma_f32 v[68:69], v[114:115], v[74:75], v[112:113]
	v_pk_fma_f32 v[70:71], v[116:117], v[72:73], v[110:111]
	s_waitcnt lgkmcnt(2)
	v_pk_mul_f32 v[72:73], v[92:93], v[68:69]
	v_pk_mul_f32 v[74:75], v[90:91], v[70:71]
	v_pk_add_f32 v[90:91], v[82:83], -1.0 op_sel_hi:[1,0]
	v_pk_add_f32 v[92:93], v[78:79], -1.0 op_sel_hi:[1,0]
	s_waitcnt lgkmcnt(1)
	v_pk_fma_f32 v[90:91], v[96:97], v[90:91], 1.0 op_sel_hi:[1,1,0]
	v_pk_fma_f32 v[92:93], v[94:95], v[92:93], 1.0 op_sel_hi:[1,1,0]
	v_pk_mul_f32 v[94:95], v[68:69], v[90:91]
	v_pk_mul_f32 v[92:93], v[70:71], v[92:93]
	v_pk_mul_f32 v[70:71], v[104:105], v[94:95]
	v_pk_mul_f32 v[68:69], v[106:107], v[92:93]
	s_waitcnt lgkmcnt(0)
	v_pk_mul_f32 v[70:71], v[100:101], v[70:71]
	v_pk_mul_f32 v[68:69], v[98:99], v[68:69]
	v_mov_b32_e32 v90, 1.0
	v_add_f32_e32 v68, v68, v69
	v_add_f32_e32 v69, v70, v71
	v_add_f32_e32 v91, v68, v69
	v_mov_b32_dpp v68, v102 row_shr:1 row_mask:0xf bank_mask:0xf bound_ctrl:1
	v_mov_b32_dpp v69, v118 row_shr:1 row_mask:0xf bank_mask:0xf bound_ctrl:1
	v_mov_b32_dpp v70, v120 row_shr:1 row_mask:0xf bank_mask:0xf bound_ctrl:1
	v_mov_b32_dpp v71, v122 row_shr:1 row_mask:0xf bank_mask:0xf bound_ctrl:1
	v_fmac_f32_e32 v68, 0xbf1b4598, v87
	v_fmac_f32_e32 v69, 0xbf1b4598, v103
	v_fmac_f32_e32 v70, 0xbf1b4598, v119
	v_fmac_f32_e32 v71, 0xbf1b4598, v121
	v_add_f32_dpp v68, v68, v68 row_shr:2 row_mask:0xf bank_mask:0xf bound_ctrl:1
	v_add_f32_dpp v69, v69, v69 row_shr:2 row_mask:0xf bank_mask:0xf bound_ctrl:1
	v_add_f32_dpp v70, v70, v70 row_shr:2 row_mask:0xf bank_mask:0xf bound_ctrl:1
	v_add_f32_dpp v71, v71, v71 row_shr:2 row_mask:0xf bank_mask:0xf bound_ctrl:1
	v_add_f32_dpp v68, v68, v68 row_shr:4 row_mask:0xf bank_mask:0xf bound_ctrl:1
	v_add_f32_dpp v69, v69, v69 row_shr:4 row_mask:0xf bank_mask:0xf bound_ctrl:1
	v_add_f32_dpp v70, v70, v70 row_shr:4 row_mask:0xf bank_mask:0xf bound_ctrl:1
	v_add_f32_dpp v71, v71, v71 row_shr:4 row_mask:0xf bank_mask:0xf bound_ctrl:1
	v_add_f32_dpp v68, v68, v68 row_shr:8 row_mask:0xf bank_mask:0xf bound_ctrl:1
	v_add_f32_dpp v69, v69, v69 row_shr:8 row_mask:0xf bank_mask:0xf bound_ctrl:1
	v_add_f32_dpp v70, v70, v70 row_shr:8 row_mask:0xf bank_mask:0xf bound_ctrl:1
	v_add_f32_dpp v71, v71, v71 row_shr:8 row_mask:0xf bank_mask:0xf bound_ctrl:1
	v_mul_f32_e32 v68, 0x3fb8aa3b, v68
	v_mul_f32_e32 v69, 0x3fb8aa3b, v69
	v_mul_f32_e32 v70, 0x3fb8aa3b, v70
	v_mul_f32_e32 v71, 0x3fb8aa3b, v71
	v_exp_f32_e32 v68, v68
	v_exp_f32_e32 v69, v69
	v_exp_f32_e32 v70, v70
	v_exp_f32_e32 v71, v71
	v_rcp_f32_e32 v100, v68
	v_rcp_f32_e32 v101, v69
	v_rcp_f32_e32 v102, v70
	v_rcp_f32_e32 v103, v71
	v_pk_mul_f32 v[96:97], v[0:1], v[72:73] op_sel_hi:[0,1]
	v_pk_mul_f32 v[98:99], v[0:1], v[74:75] op_sel_hi:[0,1]
	v_mov_b32_dpp v90, v68 row_shr:1 row_mask:0xf bank_mask:0xf
	v_pk_fma_f32 v[72:73], v[0:1], v[72:73], 0 op_sel_hi:[0,1,0] neg_lo:[1,0,0] neg_hi:[1,0,0]
	v_pk_fma_f32 v[74:75], v[0:1], v[74:75], 0 op_sel_hi:[0,1,0] neg_lo:[1,0,0] neg_hi:[1,0,0]
	v_pk_mul_f32 v[72:73], v[72:73], v[90:91] op_sel_hi:[1,0]
	v_pk_mul_f32 v[74:75], v[74:75], v[90:91] op_sel_hi:[1,0]
	v_add_f32_e32 v110, v86, v91
	v_cvt_pk_bf16_f32 v90, v74, v75
	v_cvt_pk_bf16_f32 v91, v72, v73
	v_pk_mul_f32 v[72:73], v[98:99], v[78:79]
	v_pk_mul_f32 v[74:75], v[96:97], v[82:83]
	v_pk_mul_f32 v[72:73], v[72:73], v[100:101]
	v_pk_mul_f32 v[74:75], v[74:75], v[102:103]
	v_cvt_pk_bf16_f32 v78, v72, v73
	v_cvt_pk_bf16_f32 v79, v74, v75
	v_pk_mul_f32 v[72:73], v[94:95], v[102:103]
	v_pk_mul_f32 v[74:75], v[92:93], v[100:101]
	v_cvt_pk_bf16_f32 v83, v72, v73
	v_cvt_pk_bf16_f32 v82, v74, v75
	v_pk_mul_f32 v[72:73], v[104:105], v[70:71]
	v_pk_mul_f32 v[74:75], v[106:107], v[68:69]
	ds_bpermute_b32 v0, v141, v110
	v_cvt_pk_bf16_f32 v86, v74, v75
	v_cvt_pk_bf16_f32 v87, v72, v73
	buffer_store_dwordx4 v[68:71], v214, s[52:55], s6 offen
	v_mfma_f32_16x16x16_bf16 v[68:71], v[78:79], v[150:151], 0
	s_waitcnt lgkmcnt(0)
; __device__ void phase_rwkv_dist(const Params& p, LAS unsigned char* lds, int wg, int nwg) {
;     ...
;                 bo += __shfl_xor(bo, 16); bo += __shfl_xor(bo, 32);
;                 { BON[(m * 32 + h) * 2] = bo; BON[(m * 32 + h) * 2 + 1] = 0.f; }
;     ...
;                 const bf16x8 pa0 = CAT8(qa[0], qa[1]), pa1 = CAT8(qa[2], qa[3]), pr0 = CAT8(qr[0], qr[1]), pr1 = CAT8(qr[2], qr[3]), pb0 = CAT8(qb[0], qb[1]), pb1 = CAT8(qb[2], qb[3]), pk0 = CAT8(qk[0], qk[1]), pk1 = CAT8(qk[2], qk[3]);
;     ...
;                 __builtin_amdgcn_raw_buffer_store_b128(__builtin_bit_cast(u32x4, pa0), rsWS, lane * 16, so + RC_AT, 16); __builtin_amdgcn_raw_buffer_store_b128(__builtin_bit_cast(u32x4, pa1), rsWS, lane * 16 + 1024, so + RC_AT, 16);
;                 __builtin_amdgcn_raw_buffer_store_b128(__builtin_bit_cast(u32x4, pr0), rsWS, lane * 16, so + RC_RT, 16); __builtin_amdgcn_raw_buffer_store_b128(__builtin_bit_cast(u32x4, pr1), rsWS, lane * 16 + 1024, so + RC_RT, 16);
;                 __builtin_amdgcn_sched_barrier(0);
;                 f32x4 mab = MFMA32(pb0, pa0, zero4); mab = MFMA32(pb1, pa1, mab);
;                 f32x4 mak = MFMA32(pk0, pa0, zero4); mak = MFMA32(pk1, pa1, mak);
;                 f32x4 mrb = MFMA32(pb0, pr0, zero4); mrb = MFMA32(pb1, pr1, mrb);
;                 f32x4 mrk = MFMA32(pk0, pr0, zero4); mrk = MFMA32(pk1, pr1, mrk);
; #pragma unroll
;                 for (int t = 0; t < 4; ++t) { const int j = 4 * q + t; if (!(j < r)) { mab[t] = 0.f; mak[t] = 0.f; } if (!(j <= r)) { mrb[t] = 0.f; mrk[t] = 0.f; } }
;                 { const bf16x4 e1 = pk4(mak), e2 = pk4(mrb); __builtin_amdgcn_raw_buffer_store_b128(__builtin_bit_cast(u32x4, __builtin_shufflevector(e1, e2, 0, 1, 2, 3, 4, 5, 6, 7)), rsWS, lane * 32, so + RD_MM, 16); }
;                 const bf16x4 mrkp = pk4(mrk);
;                 __builtin_amdgcn_sched_barrier(0);
;                 {   const bf16x4 nA = pk4(mab);
;                     const bf16x4 nB = pk4(MFMA16(nA, ident, zero4));
;                     f32x4 s;
; #pragma unroll
;                     for (int t = 0; t < 4; ++t) s[t] = mab[t] + ((4 * q + t == r) ? 1.f : 0.f);
;                     const bf16x4 z2a = pk4(MFMA16(nA, nB, zero4)), z2b = pk4(MFMA16(nB, nA, zero4));
;                     s = MFMA16(z2a, pk4(s), s);
;                     const bf16x4 z4a = pk4(MFMA16(z2b, z2a, zero4)), z4b = pk4(MFMA16(z2a, z2b, zero4));
	v_add_f32_e32 v0, v110, v0
	v_mfma_f32_16x16x16_bf16 v[72:75], v[82:83], v[150:151], 0
	s_nop 4
	v_cvt_pk_bf16_f32 v68, v68, v69
	v_cvt_pk_bf16_f32 v69, v70, v71
	s_nop 0
	v_cvt_pk_bf16_f32 v70, v72, v73
	v_cvt_pk_bf16_f32 v71, v74, v75
	buffer_store_dwordx4 v[68:71], v215, s[52:55], s3 offen
	ds_bpermute_b32 v68, v140, v0
	s_add_i32 s3, s2, 0x800
	s_waitcnt lgkmcnt(0)
	v_add_f32_e32 v0, v0, v68
	v_lshlrev_b64 v[68:69], 8, v[108:109]
	v_lshl_add_u64 v[68:69], s[58:59], 0, v[68:69]
	global_store_dwordx2 v[68:69], v[0:1], off
	buffer_store_dwordx4 v[64:67], v196, s[52:55], s2 offen
	buffer_store_dwordx4 v[88:91], v197, s[52:55], s2 offen
	buffer_store_dwordx4 v[60:63], v196, s[52:55], s3 offen
	buffer_store_dwordx4 v[84:87], v197, s[52:55], s3 offen
	v_mfma_f32_16x16x32_bf16 v[68:71], v[52:55], v[64:67], 0
	v_mov_b32_e32 v0, s73
	s_or_b64 vcc, s[30:31], s[22:23]
	s_addk_i32 s2, 0x2000
	v_mfma_f32_16x16x32_bf16 v[64:67], v[56:59], v[64:67], 0
	v_mfma_f32_16x16x32_bf16 v[52:55], v[52:55], v[60:63], 0
	v_mfma_f32_16x16x32_bf16 v[56:59], v[56:59], v[60:63], 0
	v_mov_b32_e32 v60, s73
	v_mfma_f32_16x16x32_bf16 v[52:55], v[76:79], v[84:87], v[52:55]
	v_mfma_f32_16x16x32_bf16 v[56:59], v[80:83], v[84:87], v[56:59]
	v_mfma_f32_16x16x32_bf16 v[64:67], v[80:83], v[88:91], v[64:67]
	s_nop 5
	v_cndmask_b32_e64 v0, v52, v0, s[24:25]
	v_cndmask_b32_e64 v60, v56, v60, s[24:25]
	v_cndmask_b32_e64 v0, v0, v52, s[22:23]
	v_mfma_f32_16x16x32_bf16 v[68:71], v[76:79], v[88:91], v[68:71]
	v_cndmask_b32_e64 v61, 0, v53, s[22:23]
	v_cndmask_b32_e64 v56, v60, v56, s[22:23]
	v_cndmask_b32_e64 v60, v54, 0, s[34:35]
	v_cndmask_b32_e64 v53, 0, v67, s[26:27]
	v_cndmask_b32_e64 v54, 0, v66, s[28:29]
	v_cndmask_b32_e64 v52, 0, v65, s[30:31]
	v_cndmask_b32_e32 v62, 0, v64, vcc
	v_cndmask_b32_e64 v55, v55, 0, s[36:37]
	v_cndmask_b32_e64 v57, 0, v57, s[22:23]
	v_cndmask_b32_e64 v58, v58, 0, s[34:35]
	v_cndmask_b32_e64 v59, v59, 0, s[36:37]
	v_cvt_pk_bf16_f32 v52, v62, v52
	v_cvt_pk_bf16_f32 v53, v54, v53
	v_cvt_pk_bf16_f32 v54, v0, v61
	v_cvt_pk_bf16_f32 v55, v60, v55
	v_cndmask_b32_e64 v71, 0, v71, s[26:27]
	v_cndmask_b32_e64 v70, 0, v70, s[28:29]
	v_cndmask_b32_e64 v69, 0, v69, s[30:31]
	v_cndmask_b32_e32 v68, 0, v68, vcc
	buffer_store_dwordx4 v[52:55], v198, s[52:55], s2 offen
	v_cvt_pk_bf16_f32 v52, v56, v57
	v_cvt_pk_bf16_f32 v53, v58, v59
	v_cvt_pk_bf16_f32 v62, v68, v69
	v_cvt_pk_bf16_f32 v63, v70, v71
	s_ashr_i32 s63, s62, 31
	s_nop 0
	v_mfma_f32_16x16x16_bf16 v[54:57], v[62:63], v[150:151], 0
	s_nop 7
	v_cvt_pk_bf16_f32 v64, v54, v55
	v_cvt_pk_bf16_f32 v65, v56, v57
	v_add_f32_e32 v54, v216, v68
	v_add_f32_e32 v55, v187, v69
	v_mfma_f32_16x16x16_bf16 v[58:61], v[62:63], v[64:65], 0
	v_add_f32_e32 v56, v217, v70
	v_add_f32_e32 v57, v188, v71
	s_nop 5
	v_cvt_pk_bf16_f32 v66, v58, v59
	v_cvt_pk_bf16_f32 v67, v60, v61
	v_mfma_f32_16x16x16_bf16 v[58:61], v[64:65], v[62:63], 0
	s_nop 7
	v_cvt_pk_bf16_f32 v62, v58, v59
	v_cvt_pk_bf16_f32 v63, v60, v61
	v_cvt_pk_bf16_f32 v58, v54, v55
	v_cvt_pk_bf16_f32 v59, v56, v57
	s_nop 1
	v_mfma_f32_16x16x16_bf16 v[54:57], v[66:67], v[58:59], v[54:57]
	v_mfma_f32_16x16x16_bf16 v[58:61], v[62:63], v[66:67], 0
	s_nop 7
	v_cvt_pk_bf16_f32 v64, v58, v59
	v_cvt_pk_bf16_f32 v65, v60, v61
	v_mfma_f32_16x16x16_bf16 v[58:61], v[66:67], v[62:63], 0
	s_nop 7
	v_cvt_pk_bf16_f32 v58, v58, v59
	v_cvt_pk_bf16_f32 v59, v60, v61
	v_cvt_pk_bf16_f32 v60, v54, v55
	v_cvt_pk_bf16_f32 v61, v56, v57
	s_nop 1
	v_mfma_f32_16x16x16_bf16 v[54:57], v[64:65], v[60:61], v[54:57]
	v_mfma_f32_16x16x16_bf16 v[58:61], v[58:59], v[64:65], 0
	s_nop 7
	v_cvt_pk_bf16_f32 v58, v58, v59
	v_cvt_pk_bf16_f32 v59, v60, v61
	v_cvt_pk_bf16_f32 v60, v54, v55
	v_cvt_pk_bf16_f32 v61, v56, v57
	s_nop 1
	v_mfma_f32_16x16x16_bf16 v[54:57], v[58:59], v[60:61], v[54:57]
	s_nop 7
	v_cvt_pk_bf16_f32 v54, v54, v55
	v_cvt_pk_bf16_f32 v55, v56, v57
	buffer_store_dwordx4 v[52:55], v199, s[52:55], s2 offen
	s_mov_b32 s90, s62

; #define RD_PEEK(cc) __hip_atomic_load(READY + bh * 512 + (cc), __ATOMIC_RELAXED, __HIP_MEMORY_SCOPE_AGENT)
; __device__ void phase_rwkv_dist(const Params& p, LAS unsigned char* lds, int wg, int nwg) {
;     ...
;             bf16_t* SS = (bf16_t*)p.out; const float* CD = (const float*)(p.ws + WS_CTL + WS_CD);
;             const int nitem = (BATCH * 32 * 64 * 32 + nwg * 64 - 1) / (nwg * 64), nstep = ((nitem + 3) / 4) * 128;
;             const int per = (nitem + 3) / 4;
;             int s2 = (unit == wg) ? 0 : nstep; f32x4 hh = zero4;
;             RD_ISSUE(fw, 0, 0u);
;             for (int c2 = fw; c2 < RC_NCHK; c2 += 8) {
;                 const unsigned pr1 = RD_PEEK(c2 + 4), pr0 = (c2 + 8 < RC_NCHK) ? RD_PEEK(c2 + 8) : 0u;
.LBB0_681:
	v_readlane_b32 s6, v253, 51
	s_cmp_lg_u32 s51, s6
	v_readlane_b32 s6, v254, 18
	v_readlane_b32 s7, v254, 19
	s_cselect_b32 s81, s56, 0
	s_andn2_b64 vcc, exec, s[6:7]
	s_cbranch_vccnz .LBB0_769
	v_writelane_b32 v254, s72, 46
	s_lshl_b32 s84, s94, 20
	v_readlane_b32 s6, v254, 14
	s_add_i32 s6, s80, s6
	s_add_i32 s7, s6, 0x2000
	buffer_load_dwordx4 v[80:83], v197, s[52:55], s7 offen sc1
	buffer_load_dwordx4 v[72:75], v196, s[52:55], s7 offen sc1
	s_add_i32 s7, s6, 0x1000
	buffer_load_dwordx4 v[88:91], v215, s[52:55], s7 offen sc1
	buffer_load_dwordx4 v[84:87], v213, s[52:55], s7 offen sc1
	buffer_load_dwordx4 v[96:99], v197, s[52:55], s7 offen sc1
	buffer_load_dwordx4 v[92:95], v196, s[52:55], s7 offen sc1
	buffer_load_dwordx4 v[64:67], v215, s[52:55], s6 offen sc1
	buffer_load_dwordx4 v[60:63], v213, s[52:55], s6 offen sc1
	buffer_load_dwordx4 v[68:71], v197, s[52:55], s6 offen sc1
	buffer_load_dwordx4 v[76:79], v196, s[52:55], s6 offen sc1
	v_readlane_b32 s7, v254, 16
	s_add_i32 s7, s84, s7
	s_add_i32 s16, s7, 0xdffff80
	v_or_b32_e32 v0, s40, v200
	s_cmp_gt_i32 s7, 0
	v_lshlrev_b32_e32 v157, 1, v0
	s_cselect_b32 s17, 0, 0xffffff80
	v_add_u32_e32 v0, s17, v157
	s_cselect_b32 s16, s16, 0xe000000
	s_add_i32 s7, s7, 0xe000000
	s_addk_i32 s6, 0x2800
	buffer_load_dwordx2 v[176:177], v0, s[52:55], s16 offen
	buffer_load_dwordx2 v[178:179], v157, s[52:55], s7 offen
	buffer_load_dwordx4 v[100:103], v202, s[52:55], s6 offen sc1
	v_readlane_b32 s6, v254, 0
	s_add_u32 s85, s6, s2
	v_readlane_b32 s2, v254, 2
	v_mov_b32_e32 v2, v1
	v_mov_b32_e32 v3, v1
	s_addc_u32 s86, s2, s3
	v_mov_b32_e32 v0, v1
	v_mov_b64_e32 v[58:59], v[2:3]
	v_readlane_b32 s2, v254, 42
	s_mov_b32 s95, s45
	v_mov_b64_e32 v[56:57], v[0:1]
	s_mov_b32 s72, s2
	v_readlane_b32 s3, v254, 43
	s_lshl_b32 s100, s72, 2
	s_add_u32 s100, s82, s100
	s_addc_u32 s101, s83, 0
	global_load_dword v229, v1, s[100:101] offset:16 sc1
	global_load_dword v230, v1, s[100:101] offset:32 sc1
	s_mov_b32 s99, 0
.LBB0_683:
	s_mov_b32 s32, 0
	s_lshl_b64 s[40:41], s[72:73], 2
	s_add_u32 s6, s82, s40
	s_addc_u32 s7, s83, s41
	s_cmpk_lt_i32 s72, 0x1f8
	s_cselect_b64 s[44:45], -1, 0
	s_cmpk_gt_i32 s72, 0x1f7
	s_cselect_b64 s[38:39], -1, 0
	s_and_b64 vcc, exec, s[38:39]
	v_mov_b32_e32 v2, 0
	v_mov_b32_e32 v3, 0
	s_cbranch_vccnz .LBB0_685

; #define RD_PEEK(cc) __hip_atomic_load(READY + bh * 512 + (cc), __ATOMIC_RELAXED, __HIP_MEMORY_SCOPE_AGENT)
; __device__ void phase_rwkv_dist(const Params& p, LAS unsigned char* lds, int wg, int nwg) {
;     ...
;                 const unsigned pr1 = RD_PEEK(c2 + 4), pr0 = (c2 + 8 < RC_NCHK) ? RD_PEEK(c2 + 8) : 0u;
;                 u32x2 raw[4]; float dd[4]; bf16_t* qq[4]; bool ok[4];
; #pragma unroll
;                 for (int k = 0; k < 4; ++k) { const int ss = s2 + k, item = fw * per + (ss >> 7), cc = ss & 127, idx = item * (nwg * 64) + wg * 64 + lane; ok[k] = ss < nstep && (ss >> 7) < per && item < nitem && idx < BATCH * 32 * 64 * 32;
;                     const int n4 = idx & 31, pp = (idx >> 5) & 63, eg = (idx >> 11) & 31, bb = idx >> 16;
;                     qq[k] = SS + ((((size_t)bb * 128 + cc) * 32 + eg) * 64 + pp) * 128 + 4 * n4; raw[k] = (u32x2){0u, 0u}; dd[k] = 0.f;
;                     if (ok[k]) { raw[k] = *(const u32x2*)qq[k]; dd[k] = CD[(bb * 128 + cc) * 32 + eg]; } }
;                 RD_ISSUE(c2 + 4, 1, pr1);
.LBB0_693:
	s_or_b64 exec, exec, s[16:17]
	s_add_i32 s100, s99, s32
	s_cmp_eq_u32 s100, 14
	s_cbranch_scc1 .Lfetch_w14
	s_cmp_eq_u32 s100, 13
	s_cbranch_scc1 .Lfetch_w13
	s_cmp_eq_u32 s100, 8
	s_cbranch_scc1 .Lfetch_w8
	s_waitcnt vmcnt(0)
	s_branch .Lfetch_wd
.Lfetch_w14:
	s_waitcnt vmcnt(14)
	s_branch .Lfetch_wd
.Lfetch_w13:
	s_waitcnt vmcnt(13)
	s_branch .Lfetch_wd

.Lfetch_wd:
	v_mov_b32_e32 v106, v229
	v_mov_b32_e32 v3, v230
	v_readfirstlane_b32 s16, v106
	s_cmp_eq_u32 s16, 0
	s_cselect_b64 s[16:17], -1, 0
	s_xor_b64 s[18:19], s[42:43], -1
	s_and_b64 s[16:17], s[18:19], s[16:17]
	s_and_b64 vcc, exec, s[16:17]
	s_cbranch_vccz .LBB0_713
	global_load_dword v104, v1, s[6:7] offset:16 sc1
	s_mov_b64 s[42:43], 0
	s_waitcnt vmcnt(0)
	v_cmp_ne_u32_e32 vcc, 0, v104
	s_cbranch_vccnz .LBB0_713
	s_sleep 2
	global_load_dword v104, v1, s[6:7] offset:16 sc1
	s_waitcnt vmcnt(0)
	v_cmp_ne_u32_e32 vcc, 0, v104
	s_cbranch_vccnz .LBB0_713
	s_mov_b32 s16, 0x80000
	s_branch .LBB0_699

.LBB0_726:
	s_bcnt1_i32_b64 s18, s[42:43]
	v_mov_b32_e32 v195, s18
	s_or_b64 exec, exec, s[16:17]
	s_andn2_b64 vcc, exec, s[44:45]
	s_add_i32 s44, s72, 8
	s_cbranch_vccnz .LBB0_725

; #define RD_PEEK(cc) __hip_atomic_load(READY + bh * 512 + (cc), __ATOMIC_RELAXED, __HIP_MEMORY_SCOPE_AGENT)
; __device__ void phase_rwkv_dist(const Params& p, LAS unsigned char* lds, int wg, int nwg) {
;     ...
;                 const unsigned pr1 = RD_PEEK(c2 + 4), pr0 = (c2 + 8 < RC_NCHK) ? RD_PEEK(c2 + 8) : 0u;
.LBB0_747:
	s_lshr_b32 s6, s44, 3
	s_mul_hi_u32 s6, s6, 0x24924925
	s_mul_i32 s6, s6, 56
	s_sub_i32 s6, s44, s6
	s_mulk_i32 s6, 0x2900
	s_add_i32 s6, s6, s80
	s_add_i32 s7, s6, 0x1000
	buffer_load_dwordx4 v[76:79], v196, s[52:55], s6 offen sc1
	buffer_load_dwordx4 v[68:71], v197, s[52:55], s6 offen sc1
	buffer_load_dwordx4 v[60:63], v213, s[52:55], s6 offen sc1
	buffer_load_dwordx4 v[64:67], v215, s[52:55], s6 offen sc1
	buffer_load_dwordx4 v[92:95], v196, s[52:55], s7 offen sc1
	buffer_load_dwordx4 v[96:99], v197, s[52:55], s7 offen sc1
	buffer_load_dwordx4 v[84:87], v213, s[52:55], s7 offen sc1
	buffer_load_dwordx4 v[88:91], v215, s[52:55], s7 offen sc1
	s_add_i32 s7, s6, 0x2000
	s_addk_i32 s6, 0x2800
	buffer_load_dwordx4 v[72:75], v196, s[52:55], s7 offen sc1
	buffer_load_dwordx4 v[80:83], v197, s[52:55], s7 offen sc1
	buffer_load_dwordx4 v[100:103], v202, s[52:55], s6 offen sc1
	s_lshl_b32 s6, s44, 11
	s_add_i32 s6, s6, s84
	s_add_i32 s7, s6, 0xe000000
	s_add_i32 s16, s6, 0xdffff80
	s_cmp_gt_i32 s6, 0
	s_cselect_b32 s6, 0, 0xffffff80
	v_add_u32_e32 v3, s6, v157
	s_cselect_b32 s6, s16, 0xe000000
	buffer_load_dwordx2 v[178:179], v157, s[52:55], s7 offen
	buffer_load_dwordx2 v[176:177], v3, s[52:55], s6 offen
	s_lshl_b32 s100, s72, 2
	s_add_u32 s100, s82, s100
	s_addc_u32 s101, s83, 0
	global_load_dword v229, v1, s[100:101] offset:48 sc1
	s_mov_b32 s98, 14
	v_mov_b32_e32 v230, 0
	s_cmpk_gt_i32 s72, 0x1ef
	s_cbranch_scc1 .Lfetch_nop0
	global_load_dword v230, v1, s[100:101] offset:64 sc1
	s_mov_b32 s98, 15
.Lfetch_nop0:
	s_mov_b64 s[42:43], -1
	s_and_b64 vcc, exec, s[46:47]
	s_cbranch_vccnz .LBB0_757

.LBB0_757:
	s_cmp_eq_u32 s98, 15
	s_cbranch_scc1 .Lfetch_s6w15
	s_cmp_eq_u32 s98, 14
	s_cbranch_scc1 .Lfetch_s6w14
	s_waitcnt vmcnt(0)
	s_branch .Lfetch_s6wd
.Lfetch_s6w15:
	s_waitcnt vmcnt(15)
	s_branch .Lfetch_s6wd
.Lfetch_s6w14:
	s_waitcnt vmcnt(14)
.Lfetch_s6wd:
	s_mov_b32 s99, 0
	v_lshlrev_b32_e32 v220, 16, v184
	v_and_b32_e32 v221, 0xffff0000, v184
	v_lshlrev_b32_e32 v184, 16, v185
	v_and_b32_e32 v185, 0xffff0000, v185
	v_lshlrev_b32_e32 v3, 16, v182
	v_and_b32_e32 v182, 0xffff0000, v182
	v_lshlrev_b32_e32 v195, 16, v183
	v_and_b32_e32 v222, 0xffff0000, v183
	s_mul_hi_u32 s6, s87, 0xaaaaaaab
	v_sub_f32_e32 v183, v182, v221
	v_sub_f32_e32 v182, v3, v220
	v_sub_f32_e32 v223, v222, v185
	v_sub_f32_e32 v222, v195, v184
	s_lshr_b32 s6, s6, 3
	v_pk_fma_f32 v[184:185], v[54:55], v[222:223], v[184:185]
	v_pk_fma_f32 v[182:183], v[52:53], v[182:183], v[220:221]
	s_mul_i32 s6, s6, 12
	v_cvt_pk_bf16_f32 v182, v182, v183
	v_cvt_pk_bf16_f32 v183, v184, v185
	s_sub_i32 s6, s87, s6
	s_mul_i32 s7, s6, 0x2b00
	s_add_i32 s7, s7, 0
	v_add_u32_e32 v3, s7, v196
	ds_write_b128 v3, v[116:119]
	ds_write_b128 v3, v[136:139] offset:1024
	ds_write_b128 v3, v[140:143] offset:2048
	ds_write_b128 v3, v[112:115] offset:3072
	ds_write_b128 v3, v[104:107] offset:4096
	ds_write_b128 v3, v[132:135] offset:5120
	ds_write_b128 v3, v[108:111] offset:6144
	ds_write_b128 v3, v[144:147] offset:7168
	ds_write_b128 v3, v[120:123] offset:8192
	ds_write_b128 v3, v[124:127] offset:9216
	v_mfma_f32_16x16x16_bf16 v[104:107], v[182:183], v[150:151], 0
	s_lshl_b32 s6, s6, 2
	v_add_u32_e32 v3, s7, v202
	s_add_i32 s6, s6, 0
	ds_write_b128 v3, v[128:131] offset:10752
	v_add_u32_e32 v3, s7, v203
	s_nop 2
	v_cvt_pk_bf16_f32 v104, v104, v105
	v_cvt_pk_bf16_f32 v105, v106, v107
	s_add_i32 s7, s72, 5
	s_add_i32 s6, s6, 0x27400
	ds_write_b64 v3, v[104:105] offset:10240
	v_mov_b32_e32 v3, s6
	v_mov_b32_e32 v104, s7
	s_mov_b64 s[6:7], exec
	s_waitcnt lgkmcnt(0)
	ds_write_b32 v3, v104
	v_mbcnt_lo_u32_b32 v3, s6, 0
	v_mbcnt_hi_u32_b32 v3, s7, v3
	v_cmp_eq_u32_e32 vcc, 0, v3
	s_and_saveexec_b64 s[16:17], vcc
	s_cbranch_execz .LBB0_759
	s_add_i32 s99, s99, 1
	s_bcnt1_i32_b64 s6, s[6:7]
	v_mov_b32_e32 v3, s6
	global_atomic_add v1, v3, s[40:41] offset:16
	global_atomic_add v1, v3, s[40:41]
	s_add_i32 s99, s99, 1

; __device__ __forceinline__ unsigned cvt_pk_bf16(float lo, float hi) { unsigned r; asm volatile("v_cvt_pk_bf16_f32 %0, %1, %2" : "=v"(r) : "v"(lo), "v"(hi)); return r; }
; __device__ void phase_rwkv_dist(const Params& p, LAS unsigned char* lds, int wg, int nwg) {
;     ...
; #pragma unroll
;                 for (int k = 0; k < 4; ++k) { if (((s2 + k) & 127) == 0) hh = zero4;
;                     if (ok[k]) { u32x2 w; w.x = pg8::cvt_pk_bf16(hh.x, hh.y); w.y = pg8::cvt_pk_bf16(hh.z, hh.w); *(u32x2*)qq[k] = w; hh = hh * dd[k] + up4(raw[k]); } }
;                 s2 += 4;
.LBB0_764:
	s_add_i32 s99, s99, 1
	v_cvt_pk_bf16_f32 v104, v56, v57
	v_cvt_pk_bf16_f32 v105, v58, v59
	global_store_dwordx2 v[158:159], v[104:105], off
	v_lshlrev_b32_e32 v104, 16, v162
	v_and_b32_e32 v105, 0xffff0000, v162
	v_lshlrev_b32_e32 v106, 16, v163
	v_and_b32_e32 v107, 0xffff0000, v163
	v_pk_fma_f32 v[58:59], v[58:59], v[2:3], v[106:107] op_sel_hi:[1,0,1]
	v_pk_fma_f32 v[56:57], v[56:57], v[2:3], v[104:105] op_sel_hi:[1,0,1]
	s_or_b64 exec, exec, s[6:7]
	s_and_saveexec_b64 s[6:7], s[62:63]
	s_cbranch_execz .LBB0_761
.LBB0_765:
	s_add_i32 s99, s99, 1
	v_cvt_pk_bf16_f32 v2, v56, v57
	v_cvt_pk_bf16_f32 v3, v58, v59
	global_store_dwordx2 v[160:161], v[2:3], off
	v_lshlrev_b32_e32 v2, 16, v168
	v_and_b32_e32 v3, 0xffff0000, v168
	v_lshlrev_b32_e32 v104, 16, v169
	v_and_b32_e32 v105, 0xffff0000, v169
	v_pk_fma_f32 v[58:59], v[164:165], v[58:59], v[104:105] op_sel_hi:[0,1,1]
	v_pk_fma_f32 v[56:57], v[164:165], v[56:57], v[2:3] op_sel_hi:[0,1,1]
	s_or_b64 exec, exec, s[6:7]
	s_and_saveexec_b64 s[6:7], s[2:3]
	s_cbranch_execz .LBB0_762
.LBB0_766:
	s_add_i32 s99, s99, 1
	v_cvt_pk_bf16_f32 v2, v56, v57
	v_cvt_pk_bf16_f32 v3, v58, v59
	global_store_dwordx2 v[166:167], v[2:3], off
	v_lshlrev_b32_e32 v2, 16, v172
	v_and_b32_e32 v3, 0xffff0000, v172
	v_lshlrev_b32_e32 v104, 16, v173
	v_and_b32_e32 v105, 0xffff0000, v173
	v_pk_fma_f32 v[58:59], v[0:1], v[58:59], v[104:105] op_sel_hi:[0,1,1]
	v_pk_fma_f32 v[56:57], v[0:1], v[56:57], v[2:3] op_sel_hi:[0,1,1]
	s_or_b64 exec, exec, s[6:7]
	s_and_saveexec_b64 s[2:3], s[60:61]
	s_cbranch_execz .LBB0_763
.LBB0_767:
	s_add_i32 s99, s99, 1
	v_cvt_pk_bf16_f32 v2, v56, v57
	v_cvt_pk_bf16_f32 v3, v58, v59
	global_store_dwordx2 v[170:171], v[2:3], off
	v_lshlrev_b32_e32 v2, 16, v180
	v_and_b32_e32 v3, 0xffff0000, v180
	v_lshlrev_b32_e32 v104, 16, v181
	v_and_b32_e32 v105, 0xffff0000, v181
	v_pk_fma_f32 v[58:59], v[174:175], v[58:59], v[104:105] op_sel_hi:[0,1,1]
	v_pk_fma_f32 v[56:57], v[174:175], v[56:57], v[2:3] op_sel_hi:[0,1,1]
	s_or_b64 exec, exec, s[2:3]
	s_add_i32 s81, s81, 4
	s_and_b64 vcc, exec, s[38:39]
	s_cbranch_vccnz .LBB0_770
